# ACT intermediate stored in 16x32 sub-tile order: FFN GEMM1 epilogue stores and FFN GEMM2 A-operand LDS-DMA fills are 1 KiB contiguous (on top of hr2)
# baseline (speedup 1.0000x reference)
.LBB0_263:
	s_waitcnt lgkmcnt(0)
	v_mul_f32_e32 v152, 0xbfb8aa3b, v174
	v_mul_f32_e32 v148, v144, v152
	v_exp_f32_e32 v150, v148
	v_mul_f32_e32 v148, v145, v152
	v_exp_f32_e32 v151, v148
	v_mul_f32_e32 v153, v146, v152
	v_mul_f32_e32 v154, v147, v152
	v_exp_f32_e32 v153, v153
	v_exp_f32_e32 v154, v154
	v_add_f32_e32 v150, 1.0, v150
	v_add_f32_e32 v151, 1.0, v151
	v_rcp_f32_e32 v150, v150
	v_rcp_f32_e32 v151, v151
	v_pk_mul_f32 v[142:143], v[146:147], v[142:143]
	v_add_f32_e32 v146, 1.0, v153
	v_add_f32_e32 v147, 1.0, v154
	v_rcp_f32_e32 v146, v146
	v_rcp_f32_e32 v147, v147
	v_lshl_or_b32 v149, s47, 7, v193
	v_lshrrev_b32_e32 v246, 4, v172
	v_mul_u32_u24_e32 v246, 0xb0, v246
	v_lshrrev_b32_e32 v247, 5, v149
	v_add_lshl_u32 v246, v246, v247, 10
	v_and_b32_e32 v247, 15, v172
	v_lshl_or_b32 v246, v247, 6, v246
	v_lshrrev_b32_e32 v247, 2, v172
	v_and_b32_e32 v247, 2, v247
	v_bfe_u32 v248, v149, 3, 2
	v_xor_b32_e32 v247, v248, v247
	v_lshl_or_b32 v246, v247, 4, v246
	v_mul_f32_e32 v148, v174, v174
	v_pk_mul_f32 v[140:141], v[144:145], v[140:141]
	v_pk_mul_f32 v[144:145], v[148:149], v[150:151] op_sel_hi:[0,1]
	v_pk_mul_f32 v[140:141], v[140:141], v[144:145]
	v_pk_mul_f32 v[144:145], v[148:149], v[146:147] op_sel_hi:[0,1]
	v_mul_f32_e32 v146, v136, v152
	v_mul_f32_e32 v147, v137, v152
	v_exp_f32_e32 v146, v146
	v_exp_f32_e32 v147, v147
	v_pk_mul_f32 v[142:143], v[142:143], v[144:145]
	v_pk_mul_f32 v[134:135], v[138:139], v[134:135]
	v_add_f32_e32 v144, 1.0, v146
	v_add_f32_e32 v145, 1.0, v147
	v_mul_f32_e32 v146, v138, v152
	v_mul_f32_e32 v147, v139, v152
	v_exp_f32_e32 v146, v146
	v_exp_f32_e32 v147, v147
	v_rcp_f32_e32 v144, v144
	v_rcp_f32_e32 v145, v145
	v_add_f32_e32 v138, 1.0, v146
	v_add_f32_e32 v139, 1.0, v147
	v_rcp_f32_e32 v138, v138
	v_rcp_f32_e32 v139, v139
	v_pk_mul_f32 v[132:133], v[136:137], v[132:133]
	v_pk_mul_f32 v[136:137], v[148:149], v[144:145] op_sel_hi:[0,1]
	v_pk_mul_f32 v[136:137], v[132:133], v[136:137]
	v_pk_mul_f32 v[132:133], v[148:149], v[138:139] op_sel_hi:[0,1]
	s_movk_i32 s6, 0x1600
	v_pk_mul_f32 v[138:139], v[134:135], v[132:133]
	v_cvt_pk_bf16_f32 v134, v136, v137
	v_nop
	v_readlane_b32 s2, v252, 55
	v_cvt_pk_bf16_f32 v132, v140, v141
	v_cvt_pk_bf16_f32 v133, v142, v143
	v_cvt_pk_bf16_f32 v135, v138, v139
	v_nop
	v_readlane_b32 s3, v252, 56
	v_pk_mul_f32 v[126:127], v[130:131], v[126:127]
	v_pk_mul_f32 v[124:125], v[128:129], v[124:125]
	v_pk_mul_f32 v[118:119], v[122:123], v[118:119]
	v_pk_mul_f32 v[116:117], v[120:121], v[116:117]
	v_pk_mul_f32 v[110:111], v[114:115], v[110:111]
	global_store_dwordx4 v246, v[132:135], s[2:3]
	v_pk_mul_f32 v[108:109], v[112:113], v[108:109]
	v_pk_mul_f32 v[102:103], v[106:107], v[102:103]
	v_mul_f32_e32 v133, 0xbfb8aa3b, v175
	v_mul_f32_e32 v132, v128, v133
	v_exp_f32_e32 v134, v132
	v_mul_f32_e32 v132, v129, v133
	v_exp_f32_e32 v135, v132
	v_mul_f32_e32 v136, v130, v133
	v_mul_f32_e32 v137, v131, v133
	v_exp_f32_e32 v136, v136
	v_exp_f32_e32 v137, v137
	v_add_f32_e32 v134, 1.0, v134
	v_add_f32_e32 v135, 1.0, v135
	v_rcp_f32_e32 v134, v134
	v_rcp_f32_e32 v135, v135
	v_add_f32_e32 v130, 1.0, v136
	v_add_f32_e32 v131, 1.0, v137
	v_rcp_f32_e32 v130, v130
	v_rcp_f32_e32 v131, v131
	v_mul_f32_e32 v132, v175, v175
	v_pk_mul_f32 v[128:129], v[132:133], v[134:135] op_sel_hi:[0,1]
	v_pk_mul_f32 v[124:125], v[124:125], v[128:129]
	v_pk_mul_f32 v[128:129], v[132:133], v[130:131] op_sel_hi:[0,1]
	v_mul_f32_e32 v130, v120, v133
	v_mul_f32_e32 v131, v121, v133
	v_exp_f32_e32 v130, v130
	v_exp_f32_e32 v131, v131
	v_pk_mul_f32 v[126:127], v[126:127], v[128:129]
	v_pk_mul_f32 v[100:101], v[104:105], v[100:101]
	v_add_f32_e32 v128, 1.0, v130
	v_add_f32_e32 v129, 1.0, v131
	v_mul_f32_e32 v130, v122, v133
	v_mul_f32_e32 v131, v123, v133
	v_exp_f32_e32 v130, v130
	v_exp_f32_e32 v131, v131
	v_rcp_f32_e32 v128, v128
	v_rcp_f32_e32 v129, v129
	v_add_f32_e32 v122, 1.0, v130
	v_add_f32_e32 v123, 1.0, v131
	v_rcp_f32_e32 v122, v122
	v_rcp_f32_e32 v123, v123
	v_pk_mul_f32 v[120:121], v[132:133], v[128:129] op_sel_hi:[0,1]
	v_pk_mul_f32 v[120:121], v[116:117], v[120:121]
	v_pk_mul_f32 v[94:95], v[98:99], v[94:95]
	v_pk_mul_f32 v[116:117], v[132:133], v[122:123] op_sel_hi:[0,1]
	v_pk_mul_f32 v[122:123], v[118:119], v[116:117]
	v_cvt_pk_bf16_f32 v118, v120, v121
	v_nop
	v_cvt_pk_bf16_f32 v116, v124, v125
	v_cvt_pk_bf16_f32 v117, v126, v127
	v_cvt_pk_bf16_f32 v119, v122, v123
	v_nop
	v_add_u32_e32 v247, 0x2c000, v246
	global_store_dwordx4 v247, v[116:119], s[2:3]
	v_pk_mul_f32 v[92:93], v[96:97], v[92:93]
	v_pk_mul_f32 v[86:87], v[90:91], v[86:87]
	v_mul_f32_e32 v117, 0xbfb8aa3b, v176
	v_mul_f32_e32 v116, v112, v117
	v_exp_f32_e32 v118, v116
	v_mul_f32_e32 v116, v113, v117
	v_exp_f32_e32 v119, v116
	v_mul_f32_e32 v120, v114, v117
	v_mul_f32_e32 v121, v115, v117
	v_exp_f32_e32 v120, v120
	v_exp_f32_e32 v121, v121
	v_add_f32_e32 v118, 1.0, v118
	v_add_f32_e32 v119, 1.0, v119
	v_rcp_f32_e32 v118, v118
	v_rcp_f32_e32 v119, v119
	v_add_f32_e32 v114, 1.0, v120
	v_add_f32_e32 v115, 1.0, v121
	v_rcp_f32_e32 v114, v114
	v_rcp_f32_e32 v115, v115
	v_mul_f32_e32 v116, v176, v176
	v_pk_mul_f32 v[112:113], v[116:117], v[118:119] op_sel_hi:[0,1]
	v_pk_mul_f32 v[108:109], v[108:109], v[112:113]
	v_pk_mul_f32 v[112:113], v[116:117], v[114:115] op_sel_hi:[0,1]
	v_mul_f32_e32 v114, v104, v117
	v_mul_f32_e32 v115, v105, v117
	v_exp_f32_e32 v114, v114
	v_exp_f32_e32 v115, v115
	v_pk_mul_f32 v[110:111], v[110:111], v[112:113]
	v_pk_mul_f32 v[84:85], v[88:89], v[84:85]
	v_add_f32_e32 v112, 1.0, v114
	v_add_f32_e32 v113, 1.0, v115
	v_mul_f32_e32 v114, v106, v117
	v_mul_f32_e32 v115, v107, v117
	v_exp_f32_e32 v114, v114
	v_exp_f32_e32 v115, v115
	v_rcp_f32_e32 v112, v112
	v_rcp_f32_e32 v113, v113
	v_add_f32_e32 v106, 1.0, v114
	v_add_f32_e32 v107, 1.0, v115
	v_rcp_f32_e32 v106, v106
	v_rcp_f32_e32 v107, v107
	v_pk_mul_f32 v[104:105], v[116:117], v[112:113] op_sel_hi:[0,1]
	v_pk_mul_f32 v[104:105], v[100:101], v[104:105]
	v_pk_mul_f32 v[78:79], v[82:83], v[78:79]
	v_pk_mul_f32 v[100:101], v[116:117], v[106:107] op_sel_hi:[0,1]
	v_pk_mul_f32 v[106:107], v[102:103], v[100:101]
	v_cvt_pk_bf16_f32 v102, v104, v105
	v_nop
	v_cvt_pk_bf16_f32 v100, v108, v109
	v_cvt_pk_bf16_f32 v101, v110, v111
	v_cvt_pk_bf16_f32 v103, v106, v107
	v_nop
	v_add_u32_e32 v247, 0x58000, v246
	global_store_dwordx4 v247, v[100:103], s[2:3]
	v_pk_mul_f32 v[76:77], v[80:81], v[76:77]
	v_pk_mul_f32 v[70:71], v[74:75], v[70:71]
	v_mul_f32_e32 v101, 0xbfb8aa3b, v177
	v_mul_f32_e32 v100, v96, v101
	v_exp_f32_e32 v102, v100
	v_mul_f32_e32 v100, v97, v101
	v_exp_f32_e32 v103, v100
	v_mul_f32_e32 v104, v98, v101
	v_mul_f32_e32 v105, v99, v101
	v_exp_f32_e32 v104, v104
	v_exp_f32_e32 v105, v105
	v_add_f32_e32 v102, 1.0, v102
	v_add_f32_e32 v103, 1.0, v103
	v_rcp_f32_e32 v102, v102
	v_rcp_f32_e32 v103, v103
	v_add_f32_e32 v98, 1.0, v104
	v_add_f32_e32 v99, 1.0, v105
	v_rcp_f32_e32 v98, v98
	v_rcp_f32_e32 v99, v99
	v_mul_f32_e32 v100, v177, v177
	v_pk_mul_f32 v[96:97], v[100:101], v[102:103] op_sel_hi:[0,1]
	v_pk_mul_f32 v[92:93], v[92:93], v[96:97]
	v_pk_mul_f32 v[96:97], v[100:101], v[98:99] op_sel_hi:[0,1]
	v_mul_f32_e32 v98, v88, v101
	v_mul_f32_e32 v99, v89, v101
	v_exp_f32_e32 v98, v98
	v_exp_f32_e32 v99, v99
	v_pk_mul_f32 v[94:95], v[94:95], v[96:97]
	v_pk_mul_f32 v[68:69], v[72:73], v[68:69]
	v_add_f32_e32 v96, 1.0, v98
	v_add_f32_e32 v97, 1.0, v99
	v_mul_f32_e32 v98, v90, v101
	v_mul_f32_e32 v99, v91, v101
	v_exp_f32_e32 v98, v98
	v_exp_f32_e32 v99, v99
	v_rcp_f32_e32 v96, v96
	v_rcp_f32_e32 v97, v97
	v_add_f32_e32 v90, 1.0, v98
	v_add_f32_e32 v91, 1.0, v99
	v_rcp_f32_e32 v90, v90
	v_rcp_f32_e32 v91, v91
	v_pk_mul_f32 v[88:89], v[100:101], v[96:97] op_sel_hi:[0,1]
	v_pk_mul_f32 v[88:89], v[84:85], v[88:89]
	v_pk_mul_f32 v[62:63], v[66:67], v[62:63]
	v_pk_mul_f32 v[84:85], v[100:101], v[90:91] op_sel_hi:[0,1]
	v_pk_mul_f32 v[90:91], v[86:87], v[84:85]
	v_cvt_pk_bf16_f32 v86, v88, v89
	v_nop
	v_cvt_pk_bf16_f32 v84, v92, v93
	v_cvt_pk_bf16_f32 v85, v94, v95
	v_cvt_pk_bf16_f32 v87, v90, v91
	v_nop
	v_add_u32_e32 v247, 0x84000, v246
	global_store_dwordx4 v247, v[84:87], s[2:3]
	v_pk_mul_f32 v[60:61], v[64:65], v[60:61]
	v_pk_mul_f32 v[54:55], v[58:59], v[54:55]
	v_mul_f32_e32 v85, 0xbfb8aa3b, v184
	v_mul_f32_e32 v84, v80, v85
	v_exp_f32_e32 v86, v84
	v_mul_f32_e32 v84, v81, v85
	v_exp_f32_e32 v87, v84
	v_mul_f32_e32 v88, v82, v85
	v_mul_f32_e32 v89, v83, v85
	v_exp_f32_e32 v88, v88
	v_exp_f32_e32 v89, v89
	v_add_f32_e32 v86, 1.0, v86
	v_add_f32_e32 v87, 1.0, v87
	v_rcp_f32_e32 v86, v86
	v_rcp_f32_e32 v87, v87
	v_add_f32_e32 v82, 1.0, v88
	v_add_f32_e32 v83, 1.0, v89
	v_rcp_f32_e32 v82, v82
	v_rcp_f32_e32 v83, v83
	v_mul_f32_e32 v84, v184, v184
	v_pk_mul_f32 v[80:81], v[84:85], v[86:87] op_sel_hi:[0,1]
	v_pk_mul_f32 v[76:77], v[76:77], v[80:81]
	v_pk_mul_f32 v[80:81], v[84:85], v[82:83] op_sel_hi:[0,1]
	v_mul_f32_e32 v82, v72, v85
	v_mul_f32_e32 v83, v73, v85
	v_exp_f32_e32 v82, v82
	v_exp_f32_e32 v83, v83
	v_pk_mul_f32 v[78:79], v[78:79], v[80:81]
	v_pk_mul_f32 v[52:53], v[56:57], v[52:53]
	v_add_f32_e32 v80, 1.0, v82
	v_add_f32_e32 v81, 1.0, v83
	v_mul_f32_e32 v82, v74, v85
	v_mul_f32_e32 v83, v75, v85
	v_exp_f32_e32 v82, v82
	v_exp_f32_e32 v83, v83
	v_rcp_f32_e32 v80, v80
	v_rcp_f32_e32 v81, v81
	v_add_f32_e32 v74, 1.0, v82
	v_add_f32_e32 v75, 1.0, v83
	v_rcp_f32_e32 v74, v74
	v_rcp_f32_e32 v75, v75
	v_pk_mul_f32 v[72:73], v[84:85], v[80:81] op_sel_hi:[0,1]
	v_pk_mul_f32 v[72:73], v[68:69], v[72:73]
	v_pk_mul_f32 v[46:47], v[50:51], v[46:47]
	v_pk_mul_f32 v[68:69], v[84:85], v[74:75] op_sel_hi:[0,1]
	v_pk_mul_f32 v[74:75], v[70:71], v[68:69]
	v_cvt_pk_bf16_f32 v70, v72, v73
	v_nop
	v_cvt_pk_bf16_f32 v68, v76, v77
	v_cvt_pk_bf16_f32 v69, v78, v79
	v_cvt_pk_bf16_f32 v71, v74, v75
	v_nop
	v_add_u32_e32 v247, 0x160000, v246
	global_store_dwordx4 v247, v[68:71], s[2:3]
	v_pk_mul_f32 v[44:45], v[48:49], v[44:45]
	v_pk_mul_f32 v[38:39], v[42:43], v[38:39]
	v_mul_f32_e32 v69, 0xbfb8aa3b, v185
	v_mul_f32_e32 v68, v64, v69
	v_exp_f32_e32 v70, v68
	v_mul_f32_e32 v68, v65, v69
	v_exp_f32_e32 v71, v68
	v_mul_f32_e32 v73, v66, v69
	v_mul_f32_e32 v74, v67, v69
	v_exp_f32_e32 v73, v73
	v_exp_f32_e32 v74, v74
	v_add_f32_e32 v70, 1.0, v70
	v_add_f32_e32 v71, 1.0, v71
	v_rcp_f32_e32 v70, v70
	v_rcp_f32_e32 v71, v71
	v_add_f32_e32 v66, 1.0, v73
	v_add_f32_e32 v67, 1.0, v74
	v_rcp_f32_e32 v66, v66
	v_rcp_f32_e32 v67, v67
	v_mul_f32_e32 v68, v185, v185
	v_pk_mul_f32 v[64:65], v[68:69], v[70:71] op_sel_hi:[0,1]
	v_pk_mul_f32 v[60:61], v[60:61], v[64:65]
	v_pk_mul_f32 v[64:65], v[68:69], v[66:67] op_sel_hi:[0,1]
	v_mul_f32_e32 v66, v56, v69
	v_mul_f32_e32 v67, v57, v69
	v_exp_f32_e32 v66, v66
	v_exp_f32_e32 v67, v67
	v_pk_mul_f32 v[62:63], v[62:63], v[64:65]
	v_pk_mul_f32 v[36:37], v[40:41], v[36:37]
	v_add_f32_e32 v64, 1.0, v66
	v_add_f32_e32 v65, 1.0, v67
	v_mul_f32_e32 v66, v58, v69
	v_mul_f32_e32 v67, v59, v69
	v_exp_f32_e32 v66, v66
	v_exp_f32_e32 v67, v67
	v_rcp_f32_e32 v64, v64
	v_rcp_f32_e32 v65, v65
	v_add_f32_e32 v58, 1.0, v66
	v_add_f32_e32 v59, 1.0, v67
	v_rcp_f32_e32 v58, v58
	v_rcp_f32_e32 v59, v59
	v_pk_mul_f32 v[56:57], v[68:69], v[64:65] op_sel_hi:[0,1]
	v_pk_mul_f32 v[56:57], v[52:53], v[56:57]
	v_pk_mul_f32 v[30:31], v[34:35], v[30:31]
	v_pk_mul_f32 v[52:53], v[68:69], v[58:59] op_sel_hi:[0,1]
	v_pk_mul_f32 v[58:59], v[54:55], v[52:53]
	v_cvt_pk_bf16_f32 v52, v60, v61
	v_cvt_pk_bf16_f32 v53, v62, v63
	v_cvt_pk_bf16_f32 v54, v56, v57
	v_cvt_pk_bf16_f32 v55, v58, v59
	v_nop
	v_add_u32_e32 v247, 0x18c000, v246
	global_store_dwordx4 v247, v[52:55], s[2:3]
	v_pk_mul_f32 v[28:29], v[32:33], v[28:29]
	v_pk_mul_f32 v[22:23], v[26:27], v[22:23]
	v_mul_f32_e32 v53, 0xbfb8aa3b, v188
	v_mul_f32_e32 v52, v48, v53
	v_exp_f32_e32 v54, v52
	v_mul_f32_e32 v52, v49, v53
	v_exp_f32_e32 v55, v52
	v_mul_f32_e32 v56, v50, v53
	v_mul_f32_e32 v57, v51, v53
	v_exp_f32_e32 v56, v56
	v_exp_f32_e32 v57, v57
	v_add_f32_e32 v54, 1.0, v54
	v_add_f32_e32 v55, 1.0, v55
	v_rcp_f32_e32 v54, v54
	v_rcp_f32_e32 v55, v55
	v_add_f32_e32 v50, 1.0, v56
	v_add_f32_e32 v51, 1.0, v57
	v_rcp_f32_e32 v50, v50
	v_rcp_f32_e32 v51, v51
	v_mul_f32_e32 v52, v188, v188
	v_pk_mul_f32 v[48:49], v[52:53], v[54:55] op_sel_hi:[0,1]
	v_pk_mul_f32 v[44:45], v[44:45], v[48:49]
	v_pk_mul_f32 v[48:49], v[52:53], v[50:51] op_sel_hi:[0,1]
	v_mul_f32_e32 v50, v40, v53
	v_mul_f32_e32 v51, v41, v53
	v_exp_f32_e32 v50, v50
	v_exp_f32_e32 v51, v51
	v_pk_mul_f32 v[46:47], v[46:47], v[48:49]
	v_pk_mul_f32 v[20:21], v[24:25], v[20:21]
	v_add_f32_e32 v48, 1.0, v50
	v_add_f32_e32 v49, 1.0, v51
	v_mul_f32_e32 v50, v42, v53
	v_mul_f32_e32 v51, v43, v53
	v_exp_f32_e32 v50, v50
	v_exp_f32_e32 v51, v51
	v_rcp_f32_e32 v48, v48
	v_rcp_f32_e32 v49, v49
	v_add_f32_e32 v42, 1.0, v50
	v_add_f32_e32 v43, 1.0, v51
	v_rcp_f32_e32 v42, v42
	v_rcp_f32_e32 v43, v43
	v_pk_mul_f32 v[40:41], v[52:53], v[48:49] op_sel_hi:[0,1]
	v_pk_mul_f32 v[40:41], v[36:37], v[40:41]
	s_andn2_b64 vcc, exec, s[36:37]
	v_pk_mul_f32 v[36:37], v[52:53], v[42:43] op_sel_hi:[0,1]
	v_pk_mul_f32 v[42:43], v[38:39], v[36:37]
	v_cvt_pk_bf16_f32 v36, v44, v45
	v_cvt_pk_bf16_f32 v37, v46, v47
	v_cvt_pk_bf16_f32 v38, v40, v41
	v_cvt_pk_bf16_f32 v39, v42, v43
	v_nop
	v_add_u32_e32 v247, 0x1b8000, v246
	global_store_dwordx4 v247, v[36:39], s[2:3]
	s_nop 1
	v_mul_f32_e32 v37, 0xbfb8aa3b, v189
	v_mul_f32_e32 v36, v32, v37
	v_exp_f32_e32 v38, v36
	v_mul_f32_e32 v36, v33, v37
	v_exp_f32_e32 v39, v36
	v_mul_f32_e32 v40, v34, v37
	v_mul_f32_e32 v41, v35, v37
	v_exp_f32_e32 v40, v40
	v_exp_f32_e32 v41, v41
	v_add_f32_e32 v38, 1.0, v38
	v_add_f32_e32 v39, 1.0, v39
	v_rcp_f32_e32 v38, v38
	v_rcp_f32_e32 v39, v39
	v_add_f32_e32 v34, 1.0, v40
	v_add_f32_e32 v35, 1.0, v41
	v_rcp_f32_e32 v34, v34
	v_rcp_f32_e32 v35, v35
	v_mul_f32_e32 v36, v189, v189
	v_pk_mul_f32 v[32:33], v[36:37], v[38:39] op_sel_hi:[0,1]
	v_pk_mul_f32 v[28:29], v[28:29], v[32:33]
	v_pk_mul_f32 v[32:33], v[36:37], v[34:35] op_sel_hi:[0,1]
	v_mul_f32_e32 v34, v24, v37
	v_mul_f32_e32 v35, v25, v37
	v_exp_f32_e32 v34, v34
	v_exp_f32_e32 v35, v35
	v_pk_mul_f32 v[30:31], v[30:31], v[32:33]
	v_add_f32_e32 v32, 1.0, v34
	v_add_f32_e32 v33, 1.0, v35
	v_mul_f32_e32 v34, v26, v37
	v_mul_f32_e32 v35, v27, v37
	v_exp_f32_e32 v34, v34
	v_exp_f32_e32 v35, v35
	v_rcp_f32_e32 v32, v32
	v_rcp_f32_e32 v33, v33
	v_add_f32_e32 v26, 1.0, v34
	v_add_f32_e32 v27, 1.0, v35
	v_rcp_f32_e32 v26, v26
	v_rcp_f32_e32 v27, v27
	v_pk_mul_f32 v[24:25], v[36:37], v[32:33] op_sel_hi:[0,1]
	v_pk_mul_f32 v[24:25], v[20:21], v[24:25]
	v_pk_mul_f32 v[20:21], v[36:37], v[26:27] op_sel_hi:[0,1]
	v_pk_mul_f32 v[26:27], v[22:23], v[20:21]
	v_cvt_pk_bf16_f32 v20, v28, v29
	v_cvt_pk_bf16_f32 v21, v30, v31
	v_cvt_pk_bf16_f32 v22, v24, v25
	v_cvt_pk_bf16_f32 v23, v26, v27
	v_nop
	v_add_u32_e32 v247, 0x1e4000, v246
	global_store_dwordx4 v247, v[20:23], s[2:3]
	s_mov_b64 s[2:3], -1
	s_cbranch_vccnz .LBB0_252
	s_andn2_b64 vcc, exec, s[0:1]
	s_cbranch_vccnz .LBB0_251
	s_barrier
	s_branch .LBB0_251

.LBB0_815:
	v_readlane_b32 s0, v254, 29
	v_readlane_b32 s1, v254, 30
	s_andn2_b64 vcc, exec, s[0:1]
	v_readfirstlane_b32 s6, v210
	s_cbranch_vccnz .LBB0_841
	v_lshlrev_b32_e32 v2, 4, v210
	s_waitcnt vmcnt(0)
	v_add_u32_e32 v4, 0x2000, v2
	v_ashrrev_i32_e32 v5, 31, v4
	v_lshrrev_b32_e32 v5, 22, v5
	v_add_u32_e32 v5, v4, v5
	v_ashrrev_i32_e32 v5, 10, v5
	v_mul_i32_i24_e32 v6, 0x400, v5
	v_sub_u32_e32 v4, v4, v6
	v_lshrrev_b32_e32 v6, 4, v4
	v_bitop3_b32 v6, v6, v4, 32 bitop3:0x6c
	s_ashr_i32 s9, s6, 6
	v_readlane_b32 s0, v255, 15
	v_ashrrev_i32_e32 v4, 31, v6
	s_lshl_b32 s16, s7, 8
	s_lshl_b32 s25, s7, 9
	s_ashr_i32 s8, s6, 8
	s_lshl_b32 s26, s9, 10
	v_readlane_b32 s1, v255, 16
	v_lshrrev_b32_e32 v4, 26, v4
	s_and_b64 s[0:1], s[0:1], exec
	v_readlane_b32 s2, v252, 55
	v_add_u32_e32 v7, v6, v4
	v_lshlrev_b32_e32 v8, 3, v5
	v_readlane_b32 s0, v252, 54
	v_readlane_b32 s3, v252, 56
	v_ashrrev_i32_e32 v4, 6, v7
	v_and_b32_e32 v8, -16, v8
	s_cselect_b32 s27, s0, s3
	v_readlane_b32 s0, v252, 53
	v_add_u32_e32 v8, v4, v8
	s_cselect_b32 s46, s0, s2
	v_and_b32_e32 v4, 3, v4
	s_mov_b32 s0, 0x7fffffe0
	v_lshrrev_b32_e32 v9, 2, v8
	v_lshlrev_b32_e32 v10, 1, v8
	v_and_or_b32 v4, v8, s0, v4
	v_and_b32_e32 v9, 4, v9
	v_and_b32_e32 v10, 24, v10
	v_or3_b32 v4, v4, v9, v10
	v_mul_lo_u32 v9, v4, s7
	v_lshlrev_b32_e32 v4, 5, v5
	v_and_b32_e32 v5, 0xc0, v7
	v_sub_u32_e32 v5, v6, v5
	v_mov_b32_e32 v13, 1
	v_ashrrev_i16_sdwa v5, v13, sext(v5) dst_sel:DWORD dst_unused:UNUSED_PAD src0_sel:DWORD src1_sel:BYTE_0
	v_and_b32_e32 v4, 32, v4
	v_bfe_i32 v5, v5, 0, 16
	v_add_u32_e32 v7, v4, v5
	v_mul_lo_u32 v6, v8, s7
	v_add_lshl_u32 v132, v9, v7, 1
	v_add_lshl_u32 v134, v7, v6, 1
	v_bfe_i32 v7, v210, 27, 1
	v_lshrrev_b32_e32 v7, 22, v7
	v_add_u32_e32 v7, v2, v7
	v_and_b32_e32 v7, 0xfffffc00, v7
	v_sub_u32_e32 v2, v2, v7
	v_lshrrev_b32_e32 v7, 4, v2
	v_ashrrev_i32_e32 v9, 31, v210
	v_bitop3_b32 v7, v7, v2, 32 bitop3:0x6c
	v_lshrrev_b32_e32 v9, 26, v9
	v_ashrrev_i32_e32 v2, 31, v7
	v_add_u32_e32 v9, v210, v9
	v_lshrrev_b32_e32 v2, 26, v2
	v_ashrrev_i32_e32 v9, 6, v9
	v_add_u32_e32 v8, v7, v2
	v_lshlrev_b32_e32 v10, 3, v9
	v_ashrrev_i32_e32 v2, 6, v8
	v_and_b32_e32 v10, -16, v10
	v_add_u32_e32 v10, v2, v10
	v_and_b32_e32 v2, 3, v2
	v_and_or_b32 v2, v10, s0, v2
	v_lshrrev_b32_e32 v11, 2, v10
	v_lshlrev_b32_e32 v12, 1, v10
	v_readlane_b32 s0, v254, 53
	v_and_b32_e32 v11, 4, v11
	v_and_b32_e32 v12, 24, v12
	v_and_b32_e32 v8, 0xc0, v8
	s_mul_hi_i32 s3, s25, s0
	s_mul_i32 s2, s25, s0
	v_readlane_b32 s0, v254, 55
	v_or3_b32 v2, v2, v11, v12
	v_sub_u32_e32 v7, v7, v8
	v_readlane_b32 s1, v254, 56
	s_mov_b32 s12, s0
	v_mul_lo_u32 v11, v2, s7
	v_lshlrev_b32_e32 v2, 5, v9
	v_ashrrev_i16_sdwa v7, v13, sext(v7) dst_sel:DWORD dst_unused:UNUSED_PAD src0_sel:DWORD src1_sel:BYTE_0
	s_mul_i32 s1, s25, s12
	v_and_b32_e32 v2, 32, v2
	v_bfe_i32 v7, v7, 0, 16
	s_mul_hi_i32 s0, s25, s0
	s_add_u32 s22, s4, s1
	v_add_u32_e32 v9, v2, v7
	s_addc_u32 s23, s5, s0
	s_add_i32 s47, s26, 0
	v_add_lshl_u32 v136, v11, v9, 1
	s_add_i32 m0, s47, 0x10000
	v_mul_lo_u32 v8, v10, s7
	global_load_lds_dwordx4 v136, s[22:23]
	s_add_i32 m0, s47, 0x12000
	s_add_u32 s0, s22, s16
	global_load_lds_dwordx4 v132, s[22:23]
	s_addc_u32 s1, s23, 0
	s_add_i32 m0, s47, 0x14000
	v_add_lshl_u32 v138, v9, v8, 1
	s_mov_b32 s101, 0
	s_movk_i32 s100, 0x80
	s_cmpk_lg_u32 s7, 0x1600
	s_cbranch_scc1 .Ltact_rowmajor
	s_movk_i32 s100, 0x800
	v_lshrrev_b32_e32 v138, 7, v210
	v_mul_u32_u24_e32 v138, 0x2c000, v138
	v_bfe_u32 v144, v210, 6, 1
	v_lshl_or_b32 v138, v144, 10, v138
	v_and_b32_e32 v144, 63, v210
	v_lshl_or_b32 v138, v144, 4, v138
	v_add_u32_e32 v134, 0xb0000, v138
.Ltact_rowmajor:
	global_load_lds_dwordx4 v136, s[0:1]
	s_add_i32 m0, s47, 0x16000
	s_add_u32 s2, s46, s2
	s_addc_u32 s3, s27, s3
	s_add_i32 s48, s47, 0x2000
	global_load_lds_dwordx4 v132, s[0:1]
	s_mov_b32 m0, s47
	s_add_u32 s12, s2, s16
	global_load_lds_dwordx4 v138, s[2:3]
	s_mov_b32 m0, s48
	s_addc_u32 s13, s3, 0
	s_add_i32 s49, s47, 0x4000
	global_load_lds_dwordx4 v134, s[2:3]
	s_mov_b32 m0, s49
	s_add_i32 s50, s47, 0x6000
	global_load_lds_dwordx4 v138, s[12:13]
	s_mov_b32 m0, s50
	v_readlane_b32 s18, v255, 9
	global_load_lds_dwordx4 v134, s[12:13]
	s_cmp_eq_u32 s8, 1
	v_readlane_b32 s19, v255, 10
	s_cselect_b64 s[12:13], -1, 0
	s_cmp_lg_u32 s8, 1
	s_mov_b32 s17, s19
	s_cbranch_scc1 .LBB0_818
	s_barrier
.LBB0_818:
	v_mov_b32_e32 v137, v3
	v_lshl_add_u64 v[10:11], s[22:23], 0, v[136:137]
	v_mov_b32_e32 v133, v3
	v_lshl_add_u64 v[12:13], s[22:23], 0, v[132:133]
	v_mov_b32_e32 v139, v3
	s_add_i32 m0, s47, 0x18000
	v_lshl_add_u64 v[10:11], v[10:11], 0, s[30:31]
	s_waitcnt lgkmcnt(0)
	v_lshl_add_u64 v[18:19], s[2:3], 0, v[138:139]
	v_mov_b32_e32 v135, v3
	s_waitcnt vmcnt(2)
	s_barrier
	global_load_lds_dwordx4 v[10:11], off
	v_lshl_add_u64 v[10:11], v[12:13], 0, s[30:31]
	s_add_i32 m0, s47, 0x1a000
	s_add_i32 s53, s47, 0x8000
	v_lshl_add_u64 v[20:21], s[2:3], 0, v[134:135]
	global_load_lds_dwordx4 v[10:11], off
	v_lshl_add_u64 v[10:11], v[18:19], 0, s[100:101]
	s_mov_b32 m0, s53
	s_add_i32 s54, s47, 0xa000
	v_lshl_add_u64 v[14:15], s[0:1], 0, v[136:137]
	global_load_lds_dwordx4 v[10:11], off
	v_lshl_add_u64 v[10:11], v[20:21], 0, s[100:101]
	s_mov_b32 m0, s54
	v_lshl_add_u64 v[16:17], s[0:1], 0, v[132:133]
	global_load_lds_dwordx4 v[10:11], off
	s_add_i32 m0, s47, 0x1c000
	v_lshl_add_u64 v[10:11], v[14:15], 0, s[30:31]
	global_load_lds_dwordx4 v[10:11], off
	v_lshl_add_u64 v[10:11], v[16:17], 0, s[30:31]
	s_add_i32 m0, s47, 0x1e000
	v_bfe_u32 v22, v210, 4, 2
	global_load_lds_dwordx4 v[10:11], off
	v_and_b32_e32 v23, 15, v210
	v_lshlrev_b32_e32 v24, 4, v22
	v_lshlrev_b32_e32 v25, 2, v210
	s_lshr_b32 s51, s7, 6
	s_and_b32 s0, s9, 3
	v_lshl_or_b32 v146, s8, 6, v23
	v_lshl_or_b32 v23, v23, 6, v24
	s_lshl_b32 s1, s8, 13
	v_and_b32_e32 v25, 32, v25
	s_add_i32 s52, s51, -2
	v_bitop3_b32 v26, v23, s1, v25 bitop3:0xde
	s_lshl_b32 s1, s0, 12
	v_add_u32_e32 v2, v8, v2
	s_cmpk_lt_u32 s6, 0x100
	v_add_lshl_u32 v2, v2, v7, 1
	v_readlane_b32 s6, v255, 9
	v_lshrrev_b32_e32 v9, 4, v210
	s_waitcnt vmcnt(6)
	s_cselect_b64 s[18:19], -1, 0
	v_lshl_add_u64 v[140:141], s[16:17], 0, v[138:139]
	v_add_u32_e32 v2, v6, v4
	v_readlane_b32 s7, v255, 10
	s_lshl_b32 s6, s0, 2
	v_bitop3_b32 v147, s1, v23, v25 bitop3:0xf6
	v_lshlrev_b32_e32 v9, 6, v9
	v_lshlrev_b32_e32 v10, 5, v22
	s_movk_i32 s1, 0xa0
	v_add_lshl_u32 v2, v2, v5, 1
	v_writelane_b32 v255, s6, 9
	s_mov_b32 s55, 0
	v_cmp_eq_u32_e64 s[36:37], 0, v22
	v_cmp_ne_u32_e64 s[38:39], 0, v22
	v_cmp_eq_u32_e64 s[40:41], 1, v22
	v_cmp_eq_u32_e64 s[42:43], 2, v22
	v_bitop3_b32 v148, v9, s1, v10 bitop3:0xc8
	s_mov_b32 s15, s14
	v_lshl_or_b32 v149, s0, 6, v24
	v_lshl_add_u64 v[142:143], s[16:17], 0, v[134:135]
	v_add_u32_e32 v150, 0, v26
	v_writelane_b32 v255, s7, 10
	v_readlane_b32 s17, v254, 54
	v_readlane_b32 s6, v254, 53
	s_barrier
	s_branch .LBB0_821

.LBB0_831:
	s_lshl_b32 s98, s100, 1
	s_add_u32 s2, s2, s100
	s_addc_u32 s3, s3, 0
	s_add_u32 s7, s22, 0x100
	v_mov_b32_e32 v4, 0
	s_addc_u32 s8, s23, 0
	s_mov_b32 s9, 0
	v_mov_b32_e32 v5, v4
	v_mov_b32_e32 v6, v4
	v_mov_b32_e32 v7, v4
	v_mov_b32_e32 v8, v4
	v_mov_b32_e32 v9, v4
	v_mov_b32_e32 v10, v4
	v_mov_b32_e32 v11, v4
	v_mov_b32_e32 v20, v4
	v_mov_b32_e32 v21, v4
	v_mov_b32_e32 v22, v4
	v_mov_b32_e32 v23, v4
	v_mov_b32_e32 v24, v4
	v_mov_b32_e32 v25, v4
	v_mov_b32_e32 v26, v4
	v_mov_b32_e32 v27, v4
	v_mov_b32_e32 v36, v4
	v_mov_b32_e32 v37, v4
	v_mov_b32_e32 v38, v4
	v_mov_b32_e32 v39, v4
	v_mov_b32_e32 v40, v4
	v_mov_b32_e32 v41, v4
	v_mov_b32_e32 v42, v4
	v_mov_b32_e32 v43, v4
	v_mov_b32_e32 v52, v4
	v_mov_b32_e32 v53, v4
	v_mov_b32_e32 v54, v4
	v_mov_b32_e32 v55, v4
	v_mov_b32_e32 v56, v4
	v_mov_b32_e32 v57, v4
	v_mov_b32_e32 v58, v4
	v_mov_b32_e32 v59, v4
	v_mov_b32_e32 v12, v4
	v_mov_b32_e32 v13, v4
	v_mov_b32_e32 v14, v4
	v_mov_b32_e32 v15, v4
	v_mov_b32_e32 v16, v4
	v_mov_b32_e32 v17, v4
	v_mov_b32_e32 v18, v4
	v_mov_b32_e32 v19, v4
	v_mov_b32_e32 v28, v4
	v_mov_b32_e32 v29, v4
	v_mov_b32_e32 v30, v4
	v_mov_b32_e32 v31, v4
	v_mov_b32_e32 v32, v4
	v_mov_b32_e32 v33, v4
	v_mov_b32_e32 v34, v4
	v_mov_b32_e32 v35, v4
	v_mov_b32_e32 v44, v4
	v_mov_b32_e32 v45, v4
	v_mov_b32_e32 v46, v4
	v_mov_b32_e32 v47, v4
	v_mov_b32_e32 v48, v4
	v_mov_b32_e32 v49, v4
	v_mov_b32_e32 v50, v4
	v_mov_b32_e32 v51, v4
	v_mov_b32_e32 v60, v4
	v_mov_b32_e32 v61, v4
	v_mov_b32_e32 v62, v4
	v_mov_b32_e32 v63, v4
	v_mov_b32_e32 v64, v4
	v_mov_b32_e32 v65, v4
	v_mov_b32_e32 v66, v4
	v_mov_b32_e32 v67, v4
	v_mov_b32_e32 v68, v4
	v_mov_b32_e32 v69, v4
	v_mov_b32_e32 v70, v4
	v_mov_b32_e32 v71, v4
	v_mov_b32_e32 v72, v4
	v_mov_b32_e32 v73, v4
	v_mov_b32_e32 v74, v4
	v_mov_b32_e32 v75, v4
	v_mov_b32_e32 v84, v4
	v_mov_b32_e32 v85, v4
	v_mov_b32_e32 v86, v4
	v_mov_b32_e32 v87, v4
	v_mov_b32_e32 v88, v4
	v_mov_b32_e32 v89, v4
	v_mov_b32_e32 v90, v4
	v_mov_b32_e32 v91, v4
	v_mov_b32_e32 v100, v4
	v_mov_b32_e32 v101, v4
	v_mov_b32_e32 v102, v4
	v_mov_b32_e32 v103, v4
	v_mov_b32_e32 v104, v4
	v_mov_b32_e32 v105, v4
	v_mov_b32_e32 v106, v4
	v_mov_b32_e32 v107, v4
	v_mov_b32_e32 v116, v4
	v_mov_b32_e32 v117, v4
	v_mov_b32_e32 v118, v4
	v_mov_b32_e32 v119, v4
	v_mov_b32_e32 v120, v4
	v_mov_b32_e32 v121, v4
	v_mov_b32_e32 v122, v4
	v_mov_b32_e32 v123, v4
	v_mov_b32_e32 v76, v4
	v_mov_b32_e32 v77, v4
	v_mov_b32_e32 v78, v4
	v_mov_b32_e32 v79, v4
	v_mov_b32_e32 v80, v4
	v_mov_b32_e32 v81, v4
	v_mov_b32_e32 v82, v4
	v_mov_b32_e32 v83, v4
	v_mov_b32_e32 v92, v4
	v_mov_b32_e32 v93, v4
	v_mov_b32_e32 v94, v4
	v_mov_b32_e32 v95, v4
	v_mov_b32_e32 v96, v4
	v_mov_b32_e32 v97, v4
	v_mov_b32_e32 v98, v4
	v_mov_b32_e32 v99, v4
	v_mov_b32_e32 v108, v4
	v_mov_b32_e32 v109, v4
	v_mov_b32_e32 v110, v4
	v_mov_b32_e32 v111, v4
	v_mov_b32_e32 v112, v4
	v_mov_b32_e32 v113, v4
	v_mov_b32_e32 v114, v4
	v_mov_b32_e32 v115, v4
	v_mov_b32_e32 v124, v4
	v_mov_b32_e32 v125, v4
	v_mov_b32_e32 v126, v4
	v_mov_b32_e32 v127, v4
	v_mov_b32_e32 v128, v4
	v_mov_b32_e32 v129, v4
	v_mov_b32_e32 v130, v4
	v_mov_b32_e32 v131, v4
.LBB0_832:
	s_add_i32 s28, s9, 2
	s_add_u32 s22, s2, s100
	s_addc_u32 s23, s3, 0
	s_add_i32 s29, 0, 0x10000
	s_cmp_eq_u32 s52, s9
	s_cselect_b32 s23, s1, s23
	s_cselect_b32 s22, s0, s22
	v_add_u32_e32 v2, s29, v147
	s_cselect_b32 s35, s21, s8
	s_cselect_b32 s34, s20, s7
	s_add_i32 s9, 0, 0x14000
	ds_read_b128 v[152:155], v2
	ds_read_b128 v[156:159], v2 offset:1024
	ds_read_b128 v[160:163], v2 offset:2048
	ds_read_b128 v[168:171], v2 offset:3072
	v_add_u32_e32 v2, s9, v147
	ds_read_b128 v[172:175], v2
	ds_read_b128 v[176:179], v2 offset:1024
	ds_read_b128 v[180:183], v2 offset:2048
	ds_read_b128 v[184:187], v2 offset:3072
	v_lshl_add_u64 v[144:145], s[2:3], 0, v[140:141]
	s_add_i32 m0, s47, 0xc000
	ds_read_b128 v[188:191], v150
	ds_read_b128 v[192:195], v150 offset:1024
	ds_read_b128 v[196:199], v150 offset:2048
	ds_read_b128 v[200:203], v150 offset:3072
	ds_read_b128 v[204:207], v150 offset:4096
	ds_read_b128 v[210:213], v150 offset:5120
	ds_read_b128 v[214:217], v150 offset:6144
	ds_read_b128 v[218:221], v150 offset:7168
	global_load_lds_dwordx4 v[144:145], off
	v_lshl_add_u64 v[144:145], s[2:3], 0, v[142:143]
	s_add_i32 m0, s47, 0xe000
	s_nop 0
	global_load_lds_dwordx4 v[144:145], off
	s_waitcnt vmcnt(8)
	s_waitcnt lgkmcnt(0)
	s_barrier
	s_setprio 1
	s_waitcnt lgkmcnt(0)
	v_mfma_f32_16x16x32_bf16 v[128:131], v[152:155], v[188:191], v[128:131]
	v_mfma_f32_16x16x32_bf16 v[124:127], v[160:163], v[188:191], v[124:127]
	v_mfma_f32_16x16x32_bf16 v[112:115], v[152:155], v[196:199], v[112:115]
	v_mfma_f32_16x16x32_bf16 v[108:111], v[160:163], v[196:199], v[108:111]
	v_mfma_f32_16x16x32_bf16 v[96:99], v[152:155], v[204:207], v[96:99]
	v_mfma_f32_16x16x32_bf16 v[92:95], v[160:163], v[204:207], v[92:95]
	v_mfma_f32_16x16x32_bf16 v[80:83], v[152:155], v[214:217], v[80:83]
	v_mfma_f32_16x16x32_bf16 v[76:79], v[160:163], v[214:217], v[76:79]
	v_mfma_f32_16x16x32_bf16 v[128:131], v[156:159], v[192:195], v[128:131]
	v_mfma_f32_16x16x32_bf16 v[124:127], v[168:171], v[192:195], v[124:127]
	v_mfma_f32_16x16x32_bf16 v[112:115], v[156:159], v[200:203], v[112:115]
	v_mfma_f32_16x16x32_bf16 v[108:111], v[168:171], v[200:203], v[108:111]
	v_mfma_f32_16x16x32_bf16 v[96:99], v[156:159], v[210:213], v[96:99]
	v_mfma_f32_16x16x32_bf16 v[92:95], v[168:171], v[210:213], v[92:95]
	v_mfma_f32_16x16x32_bf16 v[80:83], v[156:159], v[218:221], v[80:83]
	v_mfma_f32_16x16x32_bf16 v[76:79], v[168:171], v[218:221], v[76:79]
	s_setprio 0
	s_setprio 1
	v_mfma_f32_16x16x32_bf16 v[120:123], v[172:175], v[188:191], v[120:123]
	v_mfma_f32_16x16x32_bf16 v[116:119], v[180:183], v[188:191], v[116:119]
	v_mfma_f32_16x16x32_bf16 v[104:107], v[172:175], v[196:199], v[104:107]
	v_mfma_f32_16x16x32_bf16 v[100:103], v[180:183], v[196:199], v[100:103]
	v_mfma_f32_16x16x32_bf16 v[88:91], v[172:175], v[204:207], v[88:91]
	v_mfma_f32_16x16x32_bf16 v[84:87], v[180:183], v[204:207], v[84:87]
	v_mfma_f32_16x16x32_bf16 v[72:75], v[172:175], v[214:217], v[72:75]
	v_mfma_f32_16x16x32_bf16 v[68:71], v[180:183], v[214:217], v[68:71]
	v_mfma_f32_16x16x32_bf16 v[120:123], v[176:179], v[192:195], v[120:123]
	v_mfma_f32_16x16x32_bf16 v[116:119], v[184:187], v[192:195], v[116:119]
	v_mfma_f32_16x16x32_bf16 v[104:107], v[176:179], v[200:203], v[104:107]
	v_mfma_f32_16x16x32_bf16 v[100:103], v[184:187], v[200:203], v[100:103]
	v_mfma_f32_16x16x32_bf16 v[88:91], v[176:179], v[210:213], v[88:91]
	v_mfma_f32_16x16x32_bf16 v[84:87], v[184:187], v[210:213], v[84:87]
	v_mfma_f32_16x16x32_bf16 v[72:75], v[176:179], v[218:221], v[72:75]
	v_mfma_f32_16x16x32_bf16 v[68:71], v[184:187], v[218:221], v[68:71]
	s_setprio 0
	s_barrier
	s_add_i32 s29, s29, s26
	v_lshl_add_u64 v[144:145], s[34:35], 0, v[136:137]
	s_mov_b32 m0, s29
	ds_read_b128 v[188:191], v150 offset:16384
	ds_read_b128 v[192:195], v150 offset:17408
	ds_read_b128 v[196:199], v150 offset:18432
	ds_read_b128 v[200:203], v150 offset:19456
	ds_read_b128 v[204:207], v150 offset:20480
	ds_read_b128 v[210:213], v150 offset:21504
	ds_read_b128 v[214:217], v150 offset:22528
	ds_read_b128 v[218:221], v150 offset:23552
	global_load_lds_dwordx4 v[144:145], off
	s_add_i32 m0, s29, 0x2000
	v_lshl_add_u64 v[222:223], s[34:35], 0, v[132:133]
	s_add_u32 s34, s34, s16
	s_addc_u32 s35, s35, 0
	s_add_i32 s9, s9, s26
	global_load_lds_dwordx4 v[222:223], off
	v_lshl_add_u64 v[224:225], s[34:35], 0, v[136:137]
	s_mov_b32 m0, s9
	v_lshl_add_u64 v[226:227], s[34:35], 0, v[132:133]
	global_load_lds_dwordx4 v[224:225], off
	s_add_i32 m0, s9, 0x2000
	v_lshl_add_u64 v[228:229], s[22:23], 0, v[138:139]
	global_load_lds_dwordx4 v[226:227], off
	s_mov_b32 m0, s47
	v_lshl_add_u64 v[230:231], s[22:23], 0, v[134:135]
	global_load_lds_dwordx4 v[228:229], off
	s_mov_b32 m0, s48
	s_nop 0
	global_load_lds_dwordx4 v[230:231], off
	s_waitcnt vmcnt(8)
	s_waitcnt lgkmcnt(0)
	s_barrier
	s_setprio 1
	s_waitcnt lgkmcnt(0)
	v_mfma_f32_16x16x32_bf16 v[64:67], v[152:155], v[188:191], v[64:67]
	v_mfma_f32_16x16x32_bf16 v[60:63], v[160:163], v[188:191], v[60:63]
	v_mfma_f32_16x16x32_bf16 v[48:51], v[152:155], v[196:199], v[48:51]
	v_mfma_f32_16x16x32_bf16 v[44:47], v[160:163], v[196:199], v[44:47]
	v_mfma_f32_16x16x32_bf16 v[32:35], v[152:155], v[204:207], v[32:35]
	v_mfma_f32_16x16x32_bf16 v[28:31], v[160:163], v[204:207], v[28:31]
	v_mfma_f32_16x16x32_bf16 v[16:19], v[152:155], v[214:217], v[16:19]
	v_mfma_f32_16x16x32_bf16 v[12:15], v[160:163], v[214:217], v[12:15]
	v_mfma_f32_16x16x32_bf16 v[64:67], v[156:159], v[192:195], v[64:67]
	v_mfma_f32_16x16x32_bf16 v[60:63], v[168:171], v[192:195], v[60:63]
	v_mfma_f32_16x16x32_bf16 v[48:51], v[156:159], v[200:203], v[48:51]
	v_mfma_f32_16x16x32_bf16 v[44:47], v[168:171], v[200:203], v[44:47]
	v_mfma_f32_16x16x32_bf16 v[32:35], v[156:159], v[210:213], v[32:35]
	v_mfma_f32_16x16x32_bf16 v[28:31], v[168:171], v[210:213], v[28:31]
	v_mfma_f32_16x16x32_bf16 v[16:19], v[156:159], v[218:221], v[16:19]
	v_mfma_f32_16x16x32_bf16 v[12:15], v[168:171], v[218:221], v[12:15]
	s_setprio 0
	s_setprio 1
	v_mfma_f32_16x16x32_bf16 v[56:59], v[172:175], v[188:191], v[56:59]
	v_mfma_f32_16x16x32_bf16 v[52:55], v[180:183], v[188:191], v[52:55]
	v_mfma_f32_16x16x32_bf16 v[40:43], v[172:175], v[196:199], v[40:43]
	v_mfma_f32_16x16x32_bf16 v[36:39], v[180:183], v[196:199], v[36:39]
	v_mfma_f32_16x16x32_bf16 v[24:27], v[172:175], v[204:207], v[24:27]
	v_mfma_f32_16x16x32_bf16 v[20:23], v[180:183], v[204:207], v[20:23]
	v_mfma_f32_16x16x32_bf16 v[8:11], v[172:175], v[214:217], v[8:11]
	v_mfma_f32_16x16x32_bf16 v[4:7], v[180:183], v[214:217], v[4:7]
	v_mfma_f32_16x16x32_bf16 v[56:59], v[176:179], v[192:195], v[56:59]
	v_mfma_f32_16x16x32_bf16 v[52:55], v[184:187], v[192:195], v[52:55]
	v_mfma_f32_16x16x32_bf16 v[40:43], v[176:179], v[200:203], v[40:43]
	v_mfma_f32_16x16x32_bf16 v[36:39], v[184:187], v[200:203], v[36:39]
	v_mfma_f32_16x16x32_bf16 v[24:27], v[176:179], v[210:213], v[24:27]
	v_mfma_f32_16x16x32_bf16 v[20:23], v[184:187], v[210:213], v[20:23]
	v_mfma_f32_16x16x32_bf16 v[8:11], v[176:179], v[218:221], v[8:11]
	v_mfma_f32_16x16x32_bf16 v[4:7], v[184:187], v[218:221], v[4:7]
	s_setprio 0
	s_barrier
	s_add_i32 s9, 0, 0x18000
	v_add_u32_e32 v2, s9, v147
	s_add_i32 s29, 0, 0x1c000
	ds_read_b128 v[152:155], v2
	ds_read_b128 v[156:159], v2 offset:1024
	ds_read_b128 v[160:163], v2 offset:2048
	ds_read_b128 v[168:171], v2 offset:3072
	v_add_u32_e32 v2, s29, v147
	ds_read_b128 v[172:175], v2
	ds_read_b128 v[176:179], v2 offset:1024
	ds_read_b128 v[180:183], v2 offset:2048
	ds_read_b128 v[184:187], v2 offset:3072
	s_add_u32 s22, s22, s16
	s_addc_u32 s23, s23, 0
	s_mov_b32 m0, s49
	v_lshl_add_u64 v[232:233], s[22:23], 0, v[138:139]
	ds_read_b128 v[188:191], v150 offset:32768
	ds_read_b128 v[192:195], v150 offset:33792
	ds_read_b128 v[196:199], v150 offset:34816
	ds_read_b128 v[200:203], v150 offset:35840
	ds_read_b128 v[204:207], v150 offset:36864
	ds_read_b128 v[210:213], v150 offset:37888
	ds_read_b128 v[214:217], v150 offset:38912
	ds_read_b128 v[218:221], v150 offset:39936
	global_load_lds_dwordx4 v[232:233], off
	v_lshl_add_u64 v[232:233], s[22:23], 0, v[134:135]
	s_mov_b32 m0, s50
	s_nop 0
	global_load_lds_dwordx4 v[232:233], off
	s_waitcnt vmcnt(8)
	s_waitcnt lgkmcnt(0)
	s_barrier
	s_setprio 1
	s_waitcnt lgkmcnt(0)
	v_mfma_f32_16x16x32_bf16 v[128:131], v[152:155], v[188:191], v[128:131]
	v_mfma_f32_16x16x32_bf16 v[124:127], v[160:163], v[188:191], v[124:127]
	v_mfma_f32_16x16x32_bf16 v[112:115], v[152:155], v[196:199], v[112:115]
	v_mfma_f32_16x16x32_bf16 v[108:111], v[160:163], v[196:199], v[108:111]
	v_mfma_f32_16x16x32_bf16 v[96:99], v[152:155], v[204:207], v[96:99]
	v_mfma_f32_16x16x32_bf16 v[92:95], v[160:163], v[204:207], v[92:95]
	v_mfma_f32_16x16x32_bf16 v[80:83], v[152:155], v[214:217], v[80:83]
	v_mfma_f32_16x16x32_bf16 v[76:79], v[160:163], v[214:217], v[76:79]
	v_mfma_f32_16x16x32_bf16 v[128:131], v[156:159], v[192:195], v[128:131]
	v_mfma_f32_16x16x32_bf16 v[124:127], v[168:171], v[192:195], v[124:127]
	v_mfma_f32_16x16x32_bf16 v[112:115], v[156:159], v[200:203], v[112:115]
	v_mfma_f32_16x16x32_bf16 v[108:111], v[168:171], v[200:203], v[108:111]
	v_mfma_f32_16x16x32_bf16 v[96:99], v[156:159], v[210:213], v[96:99]
	v_mfma_f32_16x16x32_bf16 v[92:95], v[168:171], v[210:213], v[92:95]
	v_mfma_f32_16x16x32_bf16 v[80:83], v[156:159], v[218:221], v[80:83]
	v_mfma_f32_16x16x32_bf16 v[76:79], v[168:171], v[218:221], v[76:79]
	s_setprio 0
	s_setprio 1
	v_mfma_f32_16x16x32_bf16 v[120:123], v[172:175], v[188:191], v[120:123]
	v_mfma_f32_16x16x32_bf16 v[116:119], v[180:183], v[188:191], v[116:119]
	v_mfma_f32_16x16x32_bf16 v[104:107], v[172:175], v[196:199], v[104:107]
	v_mfma_f32_16x16x32_bf16 v[100:103], v[180:183], v[196:199], v[100:103]
	v_mfma_f32_16x16x32_bf16 v[88:91], v[172:175], v[204:207], v[88:91]
	v_mfma_f32_16x16x32_bf16 v[84:87], v[180:183], v[204:207], v[84:87]
	v_mfma_f32_16x16x32_bf16 v[72:75], v[172:175], v[214:217], v[72:75]
	v_mfma_f32_16x16x32_bf16 v[68:71], v[180:183], v[214:217], v[68:71]
	v_mfma_f32_16x16x32_bf16 v[120:123], v[176:179], v[192:195], v[120:123]
	v_mfma_f32_16x16x32_bf16 v[116:119], v[184:187], v[192:195], v[116:119]
	v_mfma_f32_16x16x32_bf16 v[104:107], v[176:179], v[200:203], v[104:107]
	v_mfma_f32_16x16x32_bf16 v[100:103], v[184:187], v[200:203], v[100:103]
	v_mfma_f32_16x16x32_bf16 v[88:91], v[176:179], v[210:213], v[88:91]
	v_mfma_f32_16x16x32_bf16 v[84:87], v[184:187], v[210:213], v[84:87]
	v_mfma_f32_16x16x32_bf16 v[72:75], v[176:179], v[218:221], v[72:75]
	v_mfma_f32_16x16x32_bf16 v[68:71], v[184:187], v[218:221], v[68:71]
	s_setprio 0
	s_barrier
	s_add_i32 s9, s9, s26
	v_lshl_add_u64 v[144:145], v[144:145], 0, s[30:31]
	s_mov_b32 m0, s9
	ds_read_b128 v[188:191], v150 offset:49152
	ds_read_b128 v[192:195], v150 offset:50176
	ds_read_b128 v[196:199], v150 offset:51200
	ds_read_b128 v[200:203], v150 offset:52224
	ds_read_b128 v[204:207], v150 offset:53248
	ds_read_b128 v[210:213], v150 offset:54272
	ds_read_b128 v[214:217], v150 offset:55296
	ds_read_b128 v[218:221], v150 offset:56320
	global_load_lds_dwordx4 v[144:145], off
	v_lshl_add_u64 v[144:145], v[222:223], 0, s[30:31]
	s_add_i32 m0, s9, 0x2000
	s_add_i32 s9, s29, s26
	global_load_lds_dwordx4 v[144:145], off
	v_lshl_add_u64 v[144:145], v[224:225], 0, s[30:31]
	s_mov_b32 m0, s9
	s_nop 0
	global_load_lds_dwordx4 v[144:145], off
	v_lshl_add_u64 v[144:145], v[226:227], 0, s[30:31]
	s_add_i32 m0, s9, 0x2000
	s_nop 0
	global_load_lds_dwordx4 v[144:145], off
	v_lshl_add_u64 v[144:145], v[228:229], 0, s[100:101]
	s_mov_b32 m0, s53
	s_nop 0
	global_load_lds_dwordx4 v[144:145], off
	v_lshl_add_u64 v[144:145], v[230:231], 0, s[100:101]
	s_mov_b32 m0, s54
	s_nop 0
	global_load_lds_dwordx4 v[144:145], off
	s_waitcnt vmcnt(8)
	s_waitcnt lgkmcnt(0)
	s_barrier
	s_setprio 1
	s_waitcnt lgkmcnt(0)
	v_mfma_f32_16x16x32_bf16 v[64:67], v[152:155], v[188:191], v[64:67]
	v_mfma_f32_16x16x32_bf16 v[60:63], v[160:163], v[188:191], v[60:63]
	v_mfma_f32_16x16x32_bf16 v[48:51], v[152:155], v[196:199], v[48:51]
	v_mfma_f32_16x16x32_bf16 v[44:47], v[160:163], v[196:199], v[44:47]
	v_mfma_f32_16x16x32_bf16 v[32:35], v[152:155], v[204:207], v[32:35]
	v_mfma_f32_16x16x32_bf16 v[28:31], v[160:163], v[204:207], v[28:31]
	v_mfma_f32_16x16x32_bf16 v[16:19], v[152:155], v[214:217], v[16:19]
	v_mfma_f32_16x16x32_bf16 v[12:15], v[160:163], v[214:217], v[12:15]
	v_mfma_f32_16x16x32_bf16 v[64:67], v[156:159], v[192:195], v[64:67]
	v_mfma_f32_16x16x32_bf16 v[60:63], v[168:171], v[192:195], v[60:63]
	v_mfma_f32_16x16x32_bf16 v[48:51], v[156:159], v[200:203], v[48:51]
	v_mfma_f32_16x16x32_bf16 v[44:47], v[168:171], v[200:203], v[44:47]
	v_mfma_f32_16x16x32_bf16 v[32:35], v[156:159], v[210:213], v[32:35]
	v_mfma_f32_16x16x32_bf16 v[28:31], v[168:171], v[210:213], v[28:31]
	v_mfma_f32_16x16x32_bf16 v[16:19], v[156:159], v[218:221], v[16:19]
	v_mfma_f32_16x16x32_bf16 v[12:15], v[168:171], v[218:221], v[12:15]
	s_setprio 0
	s_setprio 1
	v_mfma_f32_16x16x32_bf16 v[56:59], v[172:175], v[188:191], v[56:59]
	v_mfma_f32_16x16x32_bf16 v[52:55], v[180:183], v[188:191], v[52:55]
	v_mfma_f32_16x16x32_bf16 v[40:43], v[172:175], v[196:199], v[40:43]
	v_mfma_f32_16x16x32_bf16 v[36:39], v[180:183], v[196:199], v[36:39]
	v_mfma_f32_16x16x32_bf16 v[24:27], v[172:175], v[204:207], v[24:27]
	v_mfma_f32_16x16x32_bf16 v[20:23], v[180:183], v[204:207], v[20:23]
	v_mfma_f32_16x16x32_bf16 v[8:11], v[172:175], v[214:217], v[8:11]
	v_mfma_f32_16x16x32_bf16 v[4:7], v[180:183], v[214:217], v[4:7]
	v_mfma_f32_16x16x32_bf16 v[56:59], v[176:179], v[192:195], v[56:59]
	v_mfma_f32_16x16x32_bf16 v[52:55], v[184:187], v[192:195], v[52:55]
	v_mfma_f32_16x16x32_bf16 v[40:43], v[176:179], v[200:203], v[40:43]
	v_mfma_f32_16x16x32_bf16 v[36:39], v[184:187], v[200:203], v[36:39]
	v_mfma_f32_16x16x32_bf16 v[24:27], v[176:179], v[210:213], v[24:27]
	v_mfma_f32_16x16x32_bf16 v[20:23], v[184:187], v[210:213], v[20:23]
	v_mfma_f32_16x16x32_bf16 v[8:11], v[176:179], v[218:221], v[8:11]
	v_mfma_f32_16x16x32_bf16 v[4:7], v[184:187], v[218:221], v[4:7]
	s_setprio 0
	s_barrier
	s_add_u32 s2, s2, s98
	s_addc_u32 s3, s3, 0
	s_add_u32 s7, s7, 0x100
	s_addc_u32 s8, s8, 0
	s_cmp_ge_u32 s28, s51
	s_mov_b32 s9, s28
	s_cbranch_scc0 .LBB0_832
	s_and_b64 vcc, exec, s[18:19]
	s_cbranch_vccz .LBB0_835
	s_barrier
